# attention finalize staged through wave-private LDS: full-row 16B global stores instead of per-element short stores (diff + mla coop units), on top of diff interleave
# speedup vs baseline: 1.0042x; 1.0013x over previous
; __device__ __forceinline__ unsigned f2bf(float f) { return pk2(f, 0.f) & 0xffffu; }
; __device__ __forceinline__ int crow(int r, int hi) { return (r & 3) + 8 * (r >> 2) + 4 * hi; }
; __device__ __forceinline__ float xsum32(float v) { auto rr = __builtin_amdgcn_permlane32_swap(__float_as_uint(v), __float_as_uint(v), false, false); return __uint_as_float(rr[0]) + __uint_as_float(rr[1]); }
; template <bool DIFF>
; __device__ __forceinline__ void attn_unit_coop(const Grp& G, int b, int h, int qb, int n, LAS unsigned char* lds, const int tid_in) {
;     ...
;         const float lt = xsum32(st.l);
;         if (hi == 0) wsf[32 + q] = lt;
;         float inv[16];
; #pragma unroll
;         for (int r = 0; r < 16; ++r) inv[r] = 1.0f / wsf[32 + crow(r, hi)];
;         bf16* obase = (DIFF ? (n == 0 ? G.DO : G.XN) + h * 128 : G.MO + h * 64) + (seq0 + qrow0) * 1024 + q;
; #pragma unroll
;         for (int db = 0; db < NDB; ++db)
; #pragma unroll
;             for (int r = 0; r < 16; ++r) obase[(size_t)crow(r, hi) * 1024 + db * 32] = (bf16)f2bf(st.o[db][r] * inv[r]);
.LBB0_518:
	s_or_b64 exec, exec, s[2:3]
	ds_read_b128 v[68:71], v213 offset:6272
	ds_read_b128 v[72:75], v213 offset:6304
	ds_read_b128 v[76:79], v213 offset:6336
	ds_read_b128 v[94:97], v213 offset:6368
	v_readlane_b32 s98, v247, 43
	s_lshl_b32 s98, s98, 12
	s_add_i32 s98, s98, 0x14000
	v_lshlrev_b32_e32 v64, 1, v194
	v_lshl_add_u32 v64, v191, 9, v64
	v_add_u32_e32 v64, s98, v64
	v_mbcnt_lo_u32_b32 v65, -1, 0
	v_mbcnt_hi_u32_b32 v65, -1, v65
	v_lshrrev_b32_e32 v66, 3, v65
	v_and_b32_e32 v65, 7, v65
	v_lshlrev_b32_e32 v65, 4, v65
	v_lshl_add_u32 v80, v66, 7, v65
	v_add_u32_e32 v80, s98, v80
	v_lshl_add_u32 v82, v66, 11, v65
	v_add_u32_e32 v83, 0x4000, v82
	v_add_u32_e32 v84, 0x8000, v82
	v_add_u32_e32 v85, 0xc000, v82
	v_add_u32_e32 v86, 0x80, v82
	v_add_u32_e32 v87, 0x4080, v82
	v_add_u32_e32 v88, 0x8080, v82
	v_add_u32_e32 v89, 0xc080, v82
	s_lshl_b64 s[98:99], s[38:39], 11
	s_add_u32 s98, s80, s98
	s_addc_u32 s99, s81, s99
	s_waitcnt lgkmcnt(0)
	v_rcp_f32_e32 v68, v68
	v_rcp_f32_e32 v69, v69
	v_rcp_f32_e32 v70, v70
	v_rcp_f32_e32 v71, v71
	v_rcp_f32_e32 v72, v72
	v_rcp_f32_e32 v73, v73
	v_rcp_f32_e32 v74, v74
	v_rcp_f32_e32 v75, v75
	v_rcp_f32_e32 v76, v76
	v_rcp_f32_e32 v77, v77
	v_rcp_f32_e32 v78, v78
	v_rcp_f32_e32 v79, v79
	v_rcp_f32_e32 v94, v94
	v_rcp_f32_e32 v95, v95
	v_rcp_f32_e32 v96, v96
	v_rcp_f32_e32 v97, v97
	s_nop 0
	v_pk_mul_f32 v[48:49], v[48:49], v[68:69]
	v_pk_mul_f32 v[50:51], v[50:51], v[70:71]
	v_pk_mul_f32 v[52:53], v[52:53], v[72:73]
	v_pk_mul_f32 v[54:55], v[54:55], v[74:75]
	v_pk_mul_f32 v[56:57], v[56:57], v[76:77]
	v_pk_mul_f32 v[58:59], v[58:59], v[78:79]
	v_pk_mul_f32 v[60:61], v[60:61], v[94:95]
	v_pk_mul_f32 v[62:63], v[62:63], v[96:97]
	v_pk_mul_f32 v[32:33], v[32:33], v[68:69]
	v_pk_mul_f32 v[34:35], v[34:35], v[70:71]
	v_pk_mul_f32 v[36:37], v[36:37], v[72:73]
	v_pk_mul_f32 v[38:39], v[38:39], v[74:75]
	v_pk_mul_f32 v[40:41], v[40:41], v[76:77]
	v_pk_mul_f32 v[42:43], v[42:43], v[78:79]
	v_pk_mul_f32 v[44:45], v[44:45], v[94:95]
	v_pk_mul_f32 v[46:47], v[46:47], v[96:97]
	v_pk_mul_f32 v[16:17], v[16:17], v[68:69]
	v_pk_mul_f32 v[18:19], v[18:19], v[70:71]
	v_pk_mul_f32 v[20:21], v[20:21], v[72:73]
	v_pk_mul_f32 v[22:23], v[22:23], v[74:75]
	v_pk_mul_f32 v[24:25], v[24:25], v[76:77]
	v_pk_mul_f32 v[26:27], v[26:27], v[78:79]
	v_pk_mul_f32 v[28:29], v[28:29], v[94:95]
	v_pk_mul_f32 v[30:31], v[30:31], v[96:97]
	v_pk_mul_f32 v[0:1], v[0:1], v[68:69]
	v_pk_mul_f32 v[2:3], v[2:3], v[70:71]
	v_pk_mul_f32 v[4:5], v[4:5], v[72:73]
	v_pk_mul_f32 v[6:7], v[6:7], v[74:75]
	v_pk_mul_f32 v[8:9], v[8:9], v[76:77]
	v_pk_mul_f32 v[10:11], v[10:11], v[78:79]
	v_pk_mul_f32 v[12:13], v[12:13], v[94:95]
	v_pk_mul_f32 v[14:15], v[14:15], v[96:97]
	v_cvt_pk_bf16_f32 v48, v48, v49
	ds_write_b16 v64, v48 offset:0
	ds_write_b16_d16_hi v64, v48 offset:128
	v_cvt_pk_bf16_f32 v50, v50, v51
	ds_write_b16 v64, v50 offset:256
	ds_write_b16_d16_hi v64, v50 offset:384
	v_cvt_pk_bf16_f32 v52, v52, v53
	ds_write_b16 v64, v52 offset:1024
	ds_write_b16_d16_hi v64, v52 offset:1152
	v_cvt_pk_bf16_f32 v54, v54, v55
	ds_write_b16 v64, v54 offset:1280
	ds_write_b16_d16_hi v64, v54 offset:1408
	v_cvt_pk_bf16_f32 v56, v56, v57
	ds_write_b16 v64, v56 offset:2048
	ds_write_b16_d16_hi v64, v56 offset:2176
	v_cvt_pk_bf16_f32 v58, v58, v59
	ds_write_b16 v64, v58 offset:2304
	ds_write_b16_d16_hi v64, v58 offset:2432
	v_cvt_pk_bf16_f32 v60, v60, v61
	ds_write_b16 v64, v60 offset:3072
	ds_write_b16_d16_hi v64, v60 offset:3200
	v_cvt_pk_bf16_f32 v62, v62, v63
	ds_write_b16 v64, v62 offset:3328
	ds_write_b16_d16_hi v64, v62 offset:3456
	v_cvt_pk_bf16_f32 v32, v32, v33
	ds_write_b16 v64, v32 offset:64
	ds_write_b16_d16_hi v64, v32 offset:192
	v_cvt_pk_bf16_f32 v34, v34, v35
	ds_write_b16 v64, v34 offset:320
	ds_write_b16_d16_hi v64, v34 offset:448
	v_cvt_pk_bf16_f32 v36, v36, v37
	ds_write_b16 v64, v36 offset:1088
	ds_write_b16_d16_hi v64, v36 offset:1216
	v_cvt_pk_bf16_f32 v38, v38, v39
	ds_write_b16 v64, v38 offset:1344
	ds_write_b16_d16_hi v64, v38 offset:1472
	v_cvt_pk_bf16_f32 v40, v40, v41
	ds_write_b16 v64, v40 offset:2112
	ds_write_b16_d16_hi v64, v40 offset:2240
	v_cvt_pk_bf16_f32 v42, v42, v43
	ds_write_b16 v64, v42 offset:2368
	ds_write_b16_d16_hi v64, v42 offset:2496
	v_cvt_pk_bf16_f32 v44, v44, v45
	ds_write_b16 v64, v44 offset:3136
	ds_write_b16_d16_hi v64, v44 offset:3264
	v_cvt_pk_bf16_f32 v46, v46, v47
	ds_write_b16 v64, v46 offset:3392
	ds_write_b16_d16_hi v64, v46 offset:3520
	s_waitcnt lgkmcnt(0)
; __device__ __forceinline__ unsigned f2bf(float f) { return pk2(f, 0.f) & 0xffffu; }
; __device__ __forceinline__ int crow(int r, int hi) { return (r & 3) + 8 * (r >> 2) + 4 * hi; }
; template <bool DIFF>
; __device__ __forceinline__ void attn_unit_coop(const Grp& G, int b, int h, int qb, int n, LAS unsigned char* lds, const int tid_in) {
;     ...
;         bf16* obase = (DIFF ? (n == 0 ? G.DO : G.XN) + h * 128 : G.MO + h * 64) + (seq0 + qrow0) * 1024 + q;
; #pragma unroll
;         for (int db = 0; db < NDB; ++db)
; #pragma unroll
;             for (int r = 0; r < 16; ++r) obase[(size_t)crow(r, hi) * 1024 + db * 32] = (bf16)f2bf(st.o[db][r] * inv[r]);
	ds_read_b128 v[48:51], v80
	ds_read_b128 v[52:55], v80 offset:1024
	ds_read_b128 v[56:59], v80 offset:2048
	ds_read_b128 v[60:63], v80 offset:3072
	s_waitcnt lgkmcnt(3)
	global_store_dwordx4 v82, v[48:51], s[98:99]
	s_waitcnt lgkmcnt(2)
	global_store_dwordx4 v83, v[52:55], s[98:99]
	s_waitcnt lgkmcnt(1)
	global_store_dwordx4 v84, v[56:59], s[98:99]
	s_waitcnt lgkmcnt(0)
	global_store_dwordx4 v85, v[60:63], s[98:99]
	v_cvt_pk_bf16_f32 v16, v16, v17
	ds_write_b16 v64, v16 offset:0
	ds_write_b16_d16_hi v64, v16 offset:128
	v_cvt_pk_bf16_f32 v18, v18, v19
	ds_write_b16 v64, v18 offset:256
	ds_write_b16_d16_hi v64, v18 offset:384
	v_cvt_pk_bf16_f32 v20, v20, v21
	ds_write_b16 v64, v20 offset:1024
	ds_write_b16_d16_hi v64, v20 offset:1152
	v_cvt_pk_bf16_f32 v22, v22, v23
	ds_write_b16 v64, v22 offset:1280
	ds_write_b16_d16_hi v64, v22 offset:1408
	v_cvt_pk_bf16_f32 v24, v24, v25
	ds_write_b16 v64, v24 offset:2048
	ds_write_b16_d16_hi v64, v24 offset:2176
	v_cvt_pk_bf16_f32 v26, v26, v27
	ds_write_b16 v64, v26 offset:2304
	ds_write_b16_d16_hi v64, v26 offset:2432
	v_cvt_pk_bf16_f32 v28, v28, v29
	ds_write_b16 v64, v28 offset:3072
	ds_write_b16_d16_hi v64, v28 offset:3200
	v_cvt_pk_bf16_f32 v30, v30, v31
	ds_write_b16 v64, v30 offset:3328
	ds_write_b16_d16_hi v64, v30 offset:3456
	v_cvt_pk_bf16_f32 v0, v0, v1
	ds_write_b16 v64, v0 offset:64
	ds_write_b16_d16_hi v64, v0 offset:192
	v_cvt_pk_bf16_f32 v2, v2, v3
	ds_write_b16 v64, v2 offset:320
	ds_write_b16_d16_hi v64, v2 offset:448
	v_cvt_pk_bf16_f32 v4, v4, v5
	ds_write_b16 v64, v4 offset:1088
	ds_write_b16_d16_hi v64, v4 offset:1216
	v_cvt_pk_bf16_f32 v6, v6, v7
	ds_write_b16 v64, v6 offset:1344
	ds_write_b16_d16_hi v64, v6 offset:1472
	v_cvt_pk_bf16_f32 v8, v8, v9
	ds_write_b16 v64, v8 offset:2112
	ds_write_b16_d16_hi v64, v8 offset:2240
	v_cvt_pk_bf16_f32 v10, v10, v11
	ds_write_b16 v64, v10 offset:2368
	ds_write_b16_d16_hi v64, v10 offset:2496
	v_cvt_pk_bf16_f32 v12, v12, v13
	ds_write_b16 v64, v12 offset:3136
	ds_write_b16_d16_hi v64, v12 offset:3264
	v_cvt_pk_bf16_f32 v14, v14, v15
	ds_write_b16 v64, v14 offset:3392
	ds_write_b16_d16_hi v64, v14 offset:3520
	s_waitcnt lgkmcnt(0)
	ds_read_b128 v[32:35], v80
	ds_read_b128 v[36:39], v80 offset:1024
	ds_read_b128 v[40:43], v80 offset:2048
	ds_read_b128 v[44:47], v80 offset:3072
	s_waitcnt lgkmcnt(3)
	global_store_dwordx4 v86, v[32:35], s[98:99]
	s_waitcnt lgkmcnt(2)
	global_store_dwordx4 v87, v[36:39], s[98:99]
	s_waitcnt lgkmcnt(1)
	global_store_dwordx4 v88, v[40:43], s[98:99]
	s_waitcnt lgkmcnt(0)
	global_store_dwordx4 v89, v[44:47], s[98:99]
	s_mov_b64 s[0:1], 0
	s_and_b64 vcc, exec, s[36:37]
	s_nop 1
	s_cbranch_vccnz .LBB0_516

; __device__ __forceinline__ unsigned f2bf(float f) { return pk2(f, 0.f) & 0xffffu; }
; __device__ __forceinline__ int crow(int r, int hi) { return (r & 3) + 8 * (r >> 2) + 4 * hi; }
; __device__ __forceinline__ float xsum32(float v) { auto rr = __builtin_amdgcn_permlane32_swap(__float_as_uint(v), __float_as_uint(v), false, false); return __uint_as_float(rr[0]) + __uint_as_float(rr[1]); }
; template <bool DIFF>
; __device__ __forceinline__ void attn_unit_coop(const Grp& G, int b, int h, int qb, int n, LAS unsigned char* lds, const int tid_in) {
;     ...
;         const float lt = xsum32(st.l);
;         if (hi == 0) wsf[32 + q] = lt;
;         float inv[16];
; #pragma unroll
;         for (int r = 0; r < 16; ++r) inv[r] = 1.0f / wsf[32 + crow(r, hi)];
;         bf16* obase = (DIFF ? (n == 0 ? G.DO : G.XN) + h * 128 : G.MO + h * 64) + (seq0 + qrow0) * 1024 + q;
; #pragma unroll
;         for (int db = 0; db < NDB; ++db)
; #pragma unroll
;             for (int r = 0; r < 16; ++r) obase[(size_t)crow(r, hi) * 1024 + db * 32] = (bf16)f2bf(st.o[db][r] * inv[r]);
.LBB0_562:
	s_or_b64 exec, exec, s[0:1]
	ds_read_b128 v[36:39], v155 offset:6272
	ds_read_b128 v[40:43], v155 offset:6304
	ds_read_b128 v[44:47], v155 offset:6336
	ds_read_b128 v[62:65], v155 offset:6368
	s_mov_b64 s[2:3], 0
	v_readlane_b32 s98, v247, 43
	s_lshl_b32 s98, s98, 12
	s_add_i32 s98, s98, 0x14000
	v_lshlrev_b32_e32 v32, 1, v154
	v_lshl_add_u32 v32, v153, 9, v32
	v_add_u32_e32 v32, s98, v32
	v_mbcnt_lo_u32_b32 v33, -1, 0
	v_mbcnt_hi_u32_b32 v33, -1, v33
	v_lshrrev_b32_e32 v34, 3, v33
	v_and_b32_e32 v33, 7, v33
	v_lshlrev_b32_e32 v33, 4, v33
	v_lshl_add_u32 v35, v34, 7, v33
	v_add_u32_e32 v35, s98, v35
	v_lshl_add_u32 v56, v34, 11, v33
	v_add_u32_e32 v57, 0x4000, v56
	v_add_u32_e32 v58, 0x8000, v56
	v_add_u32_e32 v59, 0xc000, v56
	s_lshl_b64 s[98:99], s[30:31], 11
	s_add_u32 s98, s12, s98
	s_addc_u32 s99, s13, s99
	s_waitcnt lgkmcnt(0)
	v_rcp_f32_e32 v36, v36
	v_rcp_f32_e32 v37, v37
	v_rcp_f32_e32 v38, v38
	v_rcp_f32_e32 v39, v39
	v_rcp_f32_e32 v40, v40
	v_rcp_f32_e32 v41, v41
	v_rcp_f32_e32 v42, v42
	v_rcp_f32_e32 v43, v43
	v_rcp_f32_e32 v44, v44
	v_rcp_f32_e32 v45, v45
	v_rcp_f32_e32 v46, v46
	v_rcp_f32_e32 v47, v47
	v_rcp_f32_e32 v62, v62
	v_rcp_f32_e32 v63, v63
	v_rcp_f32_e32 v64, v64
	v_rcp_f32_e32 v65, v65
	s_nop 0
	v_pk_mul_f32 v[16:17], v[16:17], v[36:37]
	v_pk_mul_f32 v[18:19], v[18:19], v[38:39]
	v_pk_mul_f32 v[20:21], v[20:21], v[40:41]
	v_pk_mul_f32 v[22:23], v[22:23], v[42:43]
	v_pk_mul_f32 v[24:25], v[24:25], v[44:45]
	v_pk_mul_f32 v[26:27], v[26:27], v[46:47]
	v_pk_mul_f32 v[28:29], v[28:29], v[62:63]
	v_pk_mul_f32 v[30:31], v[30:31], v[64:65]
	v_pk_mul_f32 v[0:1], v[0:1], v[36:37]
	v_pk_mul_f32 v[2:3], v[2:3], v[38:39]
	v_pk_mul_f32 v[4:5], v[4:5], v[40:41]
	v_pk_mul_f32 v[6:7], v[6:7], v[42:43]
	v_pk_mul_f32 v[8:9], v[8:9], v[44:45]
	v_pk_mul_f32 v[10:11], v[10:11], v[46:47]
	v_pk_mul_f32 v[12:13], v[12:13], v[62:63]
	v_pk_mul_f32 v[14:15], v[14:15], v[64:65]
	v_cvt_pk_bf16_f32 v16, v16, v17
	ds_write_b16 v32, v16 offset:0
	ds_write_b16_d16_hi v32, v16 offset:128
	v_cvt_pk_bf16_f32 v18, v18, v19
	ds_write_b16 v32, v18 offset:256
	ds_write_b16_d16_hi v32, v18 offset:384
	v_cvt_pk_bf16_f32 v20, v20, v21
	ds_write_b16 v32, v20 offset:1024
	ds_write_b16_d16_hi v32, v20 offset:1152
	v_cvt_pk_bf16_f32 v22, v22, v23
	ds_write_b16 v32, v22 offset:1280
	ds_write_b16_d16_hi v32, v22 offset:1408
	v_cvt_pk_bf16_f32 v24, v24, v25
	ds_write_b16 v32, v24 offset:2048
	ds_write_b16_d16_hi v32, v24 offset:2176
	v_cvt_pk_bf16_f32 v26, v26, v27
	ds_write_b16 v32, v26 offset:2304
	ds_write_b16_d16_hi v32, v26 offset:2432
	v_cvt_pk_bf16_f32 v28, v28, v29
	ds_write_b16 v32, v28 offset:3072
	ds_write_b16_d16_hi v32, v28 offset:3200
	v_cvt_pk_bf16_f32 v30, v30, v31
	ds_write_b16 v32, v30 offset:3328
	ds_write_b16_d16_hi v32, v30 offset:3456
	v_cvt_pk_bf16_f32 v0, v0, v1
	ds_write_b16 v32, v0 offset:64
	ds_write_b16_d16_hi v32, v0 offset:192
	v_cvt_pk_bf16_f32 v2, v2, v3
	ds_write_b16 v32, v2 offset:320
	ds_write_b16_d16_hi v32, v2 offset:448
	v_cvt_pk_bf16_f32 v4, v4, v5
	ds_write_b16 v32, v4 offset:1088
	ds_write_b16_d16_hi v32, v4 offset:1216
	v_cvt_pk_bf16_f32 v6, v6, v7
	ds_write_b16 v32, v6 offset:1344
	ds_write_b16_d16_hi v32, v6 offset:1472
	v_cvt_pk_bf16_f32 v8, v8, v9
	ds_write_b16 v32, v8 offset:2112
	ds_write_b16_d16_hi v32, v8 offset:2240
	v_cvt_pk_bf16_f32 v10, v10, v11
	ds_write_b16 v32, v10 offset:2368
	ds_write_b16_d16_hi v32, v10 offset:2496
	v_cvt_pk_bf16_f32 v12, v12, v13
	ds_write_b16 v32, v12 offset:3136
	ds_write_b16_d16_hi v32, v12 offset:3264
	v_cvt_pk_bf16_f32 v14, v14, v15
	ds_write_b16 v32, v14 offset:3392
	ds_write_b16_d16_hi v32, v14 offset:3520
	s_waitcnt lgkmcnt(0)
	ds_read_b128 v[0:3], v35
	ds_read_b128 v[4:7], v35 offset:1024
	ds_read_b128 v[8:11], v35 offset:2048
	ds_read_b128 v[12:15], v35 offset:3072
	s_waitcnt lgkmcnt(3)
	global_store_dwordx4 v56, v[0:3], s[98:99]
	s_waitcnt lgkmcnt(2)
	global_store_dwordx4 v57, v[4:7], s[98:99]
	s_waitcnt lgkmcnt(1)
	global_store_dwordx4 v58, v[8:11], s[98:99]
	s_waitcnt lgkmcnt(0)
	global_store_dwordx4 v59, v[12:15], s[98:99]
	s_and_b64 vcc, exec, s[28:29]
	s_nop 1
	s_cbranch_vccnz .LBB0_560
